# ffn1 K-loop: LDS-DMA staging loads use the SADDR form (SGPR base + 32-bit lane offset, M0-compensated offset:128 for the K-step) instead of per-load 64-bit VALU address adds
# speedup vs baseline: 1.0012x; 1.0012x over previous
; #define PG8_STAGE(bufoff, gbase, voff) do { _Pragma("unroll") for (int _i = 0; _i < 2; ++_i) \
;         __builtin_amdgcn_global_load_lds((const unsigned*)((const char*)(gbase) + (voff)[_i]), (PG8_LAS unsigned*)(lds + (bufoff) + ldsw + _i * 8192), 16, 0, 0); } while (0)
; #define PG8_LDA(dst, b, h) do { _Pragma("unroll") for (int m = 0; m < 4; ++m) _Pragma("unroll") for (int k = 0; k < 2; ++k) dst[m][k] = *(const PG8_LAS bf16x8*)(lds + PG8_SA(b, h) + aoff + m * 2048 + k * 1024); } while (0)
; #define PG8_LDB(dst, b, h) do { _Pragma("unroll") for (int n = 0; n < 2; ++n) _Pragma("unroll") for (int k = 0; k < 2; ++k) dst[n][k] = *(const PG8_LAS bf16x8*)(lds + PG8_SB(b, h) + boff + n * 2048 + k * 1024); } while (0)
; #define PG8_MMA(ai, bj, At, Bt) do { __builtin_amdgcn_s_setprio(1); _Pragma("unroll") for (int m = 0; m < 4; ++m) _Pragma("unroll") for (int n = 0; n < 2; ++n) _Pragma("unroll") for (int k = 0; k < 2; ++k) \
;         acc[ai][bj][m][n] = __builtin_amdgcn_mfma_f32_16x16x32_bf16(Bt[n][k], At[m][k], acc[ai][bj][m][n], 0, 0, 0); __builtin_amdgcn_s_setprio(0); } while (0)
; #define PG8_WAIT_V(n) asm volatile("s_waitcnt vmcnt(" #n ")" ::: "memory")
; #define PG8_WAIT_L(n) asm volatile("s_waitcnt lgkmcnt(" #n ")" ::: "memory")
; #define PG8_BAR __builtin_amdgcn_s_barrier()
; #define PG8_SCHED __builtin_amdgcn_sched_barrier(0)
; template <class Epi, class Sched, bool ALIGN_EPI = false, bool SP2 = false>
; __device__ __forceinline__ void gemm_phase(PG8_LAS unsigned char* lds, const Gemm g, const Sched& S, const Epi& E) {
;     ...
;             PG8_LDB(B0, 0, 0); PG8_LDB(B1, 0, 1); PG8_SCHED; PG8_LDA(At, 0, 0); PG8_STAGE(PG8_SA(1, 1), a1 + hstepA, voffA);
;             PG8_WAIT_V(8); PG8_WAIT_L(0); PG8_BAR; PG8_MMA(0, 0, At, B0); PG8_MMA(0, 1, At, B1); PG8_BAR; PG8_SCHED;
;             PG8_LDA(At, 0, 1); PG8_STAGE(PG8_SB(0, 0), b2, voffB); PG8_STAGE(PG8_SB(0, 1), b2 + hstepB, voffB); PG8_STAGE(PG8_SA(0, 0), a2, voffA);
;             PG8_WAIT_V(8); PG8_WAIT_L(0); PG8_BAR; PG8_MMA(1, 0, At, B0); PG8_MMA(1, 1, At, B1); PG8_BAR; PG8_SCHED;
.LBB0_30:
	s_add_u32 s42, s38, 0xfffc0080
	s_addc_u32 s43, s39, -1
	s_add_i32 s68, 0, 0x10000
	s_cmp_eq_u32 s67, 12
	s_cselect_b32 s45, s15, s43
	s_cselect_b32 s44, s35, s42
	s_cselect_b32 s43, s13, s66
	s_cselect_b32 s42, s64, s65
	s_add_i32 s72, 0, 0x14000
	v_add_u32_e32 v54, s68, v165
	v_add_u32_e32 v164, s72, v165
	ds_read_b128 v[26:29], v54
	ds_read_b128 v[30:33], v54 offset:1024
	ds_read_b128 v[50:53], v54 offset:2048
	ds_read_b128 v[54:57], v54 offset:3072
	ds_read_b128 v[156:159], v164
	ds_read_b128 v[160:163], v164 offset:1024
	ds_read_b128 v[168:171], v164 offset:2048
	ds_read_b128 v[172:175], v164 offset:3072
	s_add_i32 m0, s49, 0xc000
	ds_read_b128 v[176:179], v166
	ds_read_b128 v[180:183], v166 offset:1024
	ds_read_b128 v[184:187], v166 offset:2048
	ds_read_b128 v[188:191], v166 offset:3072
	ds_read_b128 v[192:195], v166 offset:4096
	ds_read_b128 v[196:199], v166 offset:5120
	ds_read_b128 v[200:203], v166 offset:6144
	ds_read_b128 v[204:207], v166 offset:7168
	global_load_lds_dwordx4 v152, s[38:39]
	s_add_i32 m0, s49, 0xe000
	s_nop 0
	global_load_lds_dwordx4 v154, s[38:39]
	s_waitcnt vmcnt(8)
	s_waitcnt lgkmcnt(0)
	s_barrier
	s_setprio 1
	s_waitcnt lgkmcnt(0)
	v_mfma_f32_16x16x32_bf16 v[142:145], v[26:29], v[176:179], v[142:145]
	v_mfma_f32_16x16x32_bf16 v[138:141], v[50:53], v[176:179], v[138:141]
	v_mfma_f32_16x16x32_bf16 v[126:129], v[26:29], v[184:187], v[126:129]
	v_mfma_f32_16x16x32_bf16 v[122:125], v[50:53], v[184:187], v[122:125]
	v_mfma_f32_16x16x32_bf16 v[110:113], v[26:29], v[192:195], v[110:113]
	v_mfma_f32_16x16x32_bf16 v[106:109], v[50:53], v[192:195], v[106:109]
	v_mfma_f32_16x16x32_bf16 v[94:97], v[26:29], v[200:203], v[94:97]
	v_mfma_f32_16x16x32_bf16 v[90:93], v[50:53], v[200:203], v[90:93]
	v_mfma_f32_16x16x32_bf16 v[142:145], v[30:33], v[180:183], v[142:145]
	v_mfma_f32_16x16x32_bf16 v[138:141], v[54:57], v[180:183], v[138:141]
	v_mfma_f32_16x16x32_bf16 v[126:129], v[30:33], v[188:191], v[126:129]
	v_mfma_f32_16x16x32_bf16 v[122:125], v[54:57], v[188:191], v[122:125]
	v_mfma_f32_16x16x32_bf16 v[110:113], v[30:33], v[196:199], v[110:113]
	v_mfma_f32_16x16x32_bf16 v[106:109], v[54:57], v[196:199], v[106:109]
	v_mfma_f32_16x16x32_bf16 v[94:97], v[30:33], v[204:207], v[94:97]
	v_mfma_f32_16x16x32_bf16 v[90:93], v[54:57], v[204:207], v[90:93]
	s_setprio 0
	s_setprio 1
	v_mfma_f32_16x16x32_bf16 v[134:137], v[156:159], v[176:179], v[134:137]
	v_mfma_f32_16x16x32_bf16 v[130:133], v[168:171], v[176:179], v[130:133]
	v_mfma_f32_16x16x32_bf16 v[118:121], v[156:159], v[184:187], v[118:121]
	v_mfma_f32_16x16x32_bf16 v[114:117], v[168:171], v[184:187], v[114:117]
	v_mfma_f32_16x16x32_bf16 v[102:105], v[156:159], v[192:195], v[102:105]
	v_mfma_f32_16x16x32_bf16 v[98:101], v[168:171], v[192:195], v[98:101]
	v_mfma_f32_16x16x32_bf16 v[86:89], v[156:159], v[200:203], v[86:89]
	v_mfma_f32_16x16x32_bf16 v[82:85], v[168:171], v[200:203], v[82:85]
	v_mfma_f32_16x16x32_bf16 v[134:137], v[160:163], v[180:183], v[134:137]
	v_mfma_f32_16x16x32_bf16 v[130:133], v[172:175], v[180:183], v[130:133]
	v_mfma_f32_16x16x32_bf16 v[118:121], v[160:163], v[188:191], v[118:121]
	v_mfma_f32_16x16x32_bf16 v[114:117], v[172:175], v[188:191], v[114:117]
	v_mfma_f32_16x16x32_bf16 v[102:105], v[160:163], v[196:199], v[102:105]
	v_mfma_f32_16x16x32_bf16 v[98:101], v[172:175], v[196:199], v[98:101]
	v_mfma_f32_16x16x32_bf16 v[86:89], v[160:163], v[204:207], v[86:89]
	v_mfma_f32_16x16x32_bf16 v[82:85], v[172:175], v[204:207], v[82:85]
	s_setprio 0
	s_barrier
	s_add_i32 s68, s68, s47
	s_mov_b32 m0, s68
	ds_read_b128 v[176:179], v166 offset:16384
	ds_read_b128 v[180:183], v166 offset:17408
	ds_read_b128 v[184:187], v166 offset:18432
	ds_read_b128 v[188:191], v166 offset:19456
	ds_read_b128 v[192:195], v166 offset:20480
	ds_read_b128 v[196:199], v166 offset:21504
	ds_read_b128 v[200:203], v166 offset:22528
	ds_read_b128 v[204:207], v166 offset:23552
	global_load_lds_dwordx4 v0, s[42:43]
	s_add_i32 m0, s68, 0x2000
	s_add_u32 s68, s42, 0x40000
	s_addc_u32 s69, s43, 0
	s_add_i32 s72, s72, s47
	global_load_lds_dwordx4 v146, s[42:43]
	s_mov_b32 m0, s72
	s_nop 0
	global_load_lds_dwordx4 v0, s[68:69]
	s_add_i32 m0, s72, 0x2000
	s_nop 0
	global_load_lds_dwordx4 v146, s[68:69]
	s_mov_b32 m0, s49
	s_nop 0
	global_load_lds_dwordx4 v150, s[44:45]
	s_mov_b32 m0, s50
	s_nop 0
	global_load_lds_dwordx4 v148, s[44:45]
	s_waitcnt vmcnt(8)
	s_waitcnt lgkmcnt(0)
	s_barrier
	s_setprio 1
	s_waitcnt lgkmcnt(0)
	v_mfma_f32_16x16x32_bf16 v[78:81], v[26:29], v[176:179], v[78:81]
	v_mfma_f32_16x16x32_bf16 v[74:77], v[50:53], v[176:179], v[74:77]
	v_mfma_f32_16x16x32_bf16 v[66:69], v[26:29], v[184:187], v[66:69]
	v_mfma_f32_16x16x32_bf16 v[58:61], v[50:53], v[184:187], v[58:61]
	v_mfma_f32_16x16x32_bf16 v[42:45], v[26:29], v[192:195], v[42:45]
	v_mfma_f32_16x16x32_bf16 v[34:37], v[50:53], v[192:195], v[34:37]
	v_mfma_f32_16x16x32_bf16 v[18:21], v[26:29], v[200:203], v[18:21]
	v_mfma_f32_16x16x32_bf16 v[10:13], v[50:53], v[200:203], v[10:13]
	v_mfma_f32_16x16x32_bf16 v[78:81], v[30:33], v[180:183], v[78:81]
	v_mfma_f32_16x16x32_bf16 v[74:77], v[54:57], v[180:183], v[74:77]
	v_mfma_f32_16x16x32_bf16 v[66:69], v[30:33], v[188:191], v[66:69]
	v_mfma_f32_16x16x32_bf16 v[58:61], v[54:57], v[188:191], v[58:61]
	v_mfma_f32_16x16x32_bf16 v[42:45], v[30:33], v[196:199], v[42:45]
	v_mfma_f32_16x16x32_bf16 v[34:37], v[54:57], v[196:199], v[34:37]
	v_mfma_f32_16x16x32_bf16 v[18:21], v[30:33], v[204:207], v[18:21]
	v_mfma_f32_16x16x32_bf16 v[10:13], v[54:57], v[204:207], v[10:13]
	s_setprio 0
	s_setprio 1
	v_mfma_f32_16x16x32_bf16 v[46:49], v[156:159], v[184:187], v[46:49]
	v_mfma_f32_16x16x32_bf16 v[38:41], v[168:171], v[184:187], v[38:41]
	v_mfma_f32_16x16x32_bf16 v[22:25], v[156:159], v[192:195], v[22:25]
	v_mfma_f32_16x16x32_bf16 v[14:17], v[168:171], v[192:195], v[14:17]
	v_mfma_f32_16x16x32_bf16 v[6:9], v[156:159], v[200:203], v[6:9]
	v_mfma_f32_16x16x32_bf16 v[2:5], v[168:171], v[200:203], v[2:5]
	v_mfma_f32_16x16x32_bf16 v[26:29], v[156:159], v[176:179], v[70:73]
	v_mfma_f32_16x16x32_bf16 v[30:33], v[168:171], v[176:179], v[62:65]
	v_mfma_f32_16x16x32_bf16 v[46:49], v[160:163], v[188:191], v[46:49]
	v_mfma_f32_16x16x32_bf16 v[38:41], v[172:175], v[188:191], v[38:41]
	v_mfma_f32_16x16x32_bf16 v[22:25], v[160:163], v[196:199], v[22:25]
	v_mfma_f32_16x16x32_bf16 v[14:17], v[172:175], v[196:199], v[14:17]
	v_mfma_f32_16x16x32_bf16 v[6:9], v[160:163], v[204:207], v[6:9]
	v_mfma_f32_16x16x32_bf16 v[2:5], v[172:175], v[204:207], v[2:5]
	v_mfma_f32_16x16x32_bf16 v[26:29], v[160:163], v[180:183], v[26:29]
	v_mfma_f32_16x16x32_bf16 v[30:33], v[172:175], v[180:183], v[30:33]
	s_setprio 0
	s_barrier
; #define PG8_STAGE(bufoff, gbase, voff) do { _Pragma("unroll") for (int _i = 0; _i < 2; ++_i) \
;         __builtin_amdgcn_global_load_lds((const unsigned*)((const char*)(gbase) + (voff)[_i]), (PG8_LAS unsigned*)(lds + (bufoff) + ldsw + _i * 8192), 16, 0, 0); } while (0)
; #define PG8_LDA(dst, b, h) do { _Pragma("unroll") for (int m = 0; m < 4; ++m) _Pragma("unroll") for (int k = 0; k < 2; ++k) dst[m][k] = *(const PG8_LAS bf16x8*)(lds + PG8_SA(b, h) + aoff + m * 2048 + k * 1024); } while (0)
; #define PG8_LDB(dst, b, h) do { _Pragma("unroll") for (int n = 0; n < 2; ++n) _Pragma("unroll") for (int k = 0; k < 2; ++k) dst[n][k] = *(const PG8_LAS bf16x8*)(lds + PG8_SB(b, h) + boff + n * 2048 + k * 1024); } while (0)
; #define PG8_MMA(ai, bj, At, Bt) do { __builtin_amdgcn_s_setprio(1); _Pragma("unroll") for (int m = 0; m < 4; ++m) _Pragma("unroll") for (int n = 0; n < 2; ++n) _Pragma("unroll") for (int k = 0; k < 2; ++k) \
;         acc[ai][bj][m][n] = __builtin_amdgcn_mfma_f32_16x16x32_bf16(Bt[n][k], At[m][k], acc[ai][bj][m][n], 0, 0, 0); __builtin_amdgcn_s_setprio(0); } while (0)
; #define PG8_WAIT_V(n) asm volatile("s_waitcnt vmcnt(" #n ")" ::: "memory")
; #define PG8_WAIT_L(n) asm volatile("s_waitcnt lgkmcnt(" #n ")" ::: "memory")
; #define PG8_BAR __builtin_amdgcn_s_barrier()
; #define PG8_SCHED __builtin_amdgcn_sched_barrier(0)
; template <class Epi, class Sched, bool ALIGN_EPI = false, bool SP2 = false>
; __device__ __forceinline__ void gemm_phase(PG8_LAS unsigned char* lds, const Gemm g, const Sched& S, const Epi& E) {
;     ...
;             PG8_LDB(B0, 1, 0); PG8_LDB(B1, 1, 1); PG8_SCHED; PG8_LDA(At, 1, 0); PG8_STAGE(PG8_SA(0, 1), a2 + hstepA, voffA);
;             PG8_WAIT_V(8); PG8_WAIT_L(0); PG8_BAR; PG8_MMA(0, 0, At, B0); PG8_MMA(0, 1, At, B1); PG8_BAR; PG8_SCHED;
;             PG8_LDA(At, 1, 1); PG8_STAGE(PG8_SB(1, 0), b3, voffB); PG8_STAGE(PG8_SB(1, 1), b3 + hstepB, voffB); PG8_STAGE(PG8_SA(1, 0), a3, voffA);
;             PG8_WAIT_V(8); PG8_WAIT_L(0); PG8_BAR; PG8_MMA(1, 0, At, B0); PG8_MMA(1, 1, At, B1); PG8_BAR; PG8_SCHED;
	s_add_i32 s68, 0, 0x18000
	s_add_i32 s69, 0, 0x1c000
	v_add_u32_e32 v70, s68, v165
	v_add_u32_e32 v164, s69, v165
	ds_read_b128 v[50:53], v70
	ds_read_b128 v[54:57], v70 offset:1024
	ds_read_b128 v[62:65], v70 offset:2048
	ds_read_b128 v[70:73], v70 offset:3072
	ds_read_b128 v[156:159], v164
	ds_read_b128 v[160:163], v164 offset:1024
	ds_read_b128 v[168:171], v164 offset:2048
	ds_read_b128 v[172:175], v164 offset:3072
	s_add_u32 s100, s44, 0x40000
	s_addc_u32 s101, s45, 0
	s_mov_b32 m0, s51
	ds_read_b128 v[176:179], v166 offset:32768
	ds_read_b128 v[180:183], v166 offset:33792
	ds_read_b128 v[184:187], v166 offset:34816
	ds_read_b128 v[188:191], v166 offset:35840
	ds_read_b128 v[192:195], v166 offset:36864
	ds_read_b128 v[196:199], v166 offset:37888
	ds_read_b128 v[200:203], v166 offset:38912
	ds_read_b128 v[204:207], v166 offset:39936
	global_load_lds_dwordx4 v150, s[100:101]
	s_mov_b32 m0, s52
	s_nop 0
	global_load_lds_dwordx4 v148, s[100:101]
	s_waitcnt vmcnt(8)
	s_waitcnt lgkmcnt(0)
	s_barrier
	s_setprio 1
	s_waitcnt lgkmcnt(0)
	v_mfma_f32_16x16x32_bf16 v[142:145], v[50:53], v[176:179], v[142:145]
	v_mfma_f32_16x16x32_bf16 v[138:141], v[62:65], v[176:179], v[138:141]
	v_mfma_f32_16x16x32_bf16 v[126:129], v[50:53], v[184:187], v[126:129]
	v_mfma_f32_16x16x32_bf16 v[122:125], v[62:65], v[184:187], v[122:125]
	v_mfma_f32_16x16x32_bf16 v[110:113], v[50:53], v[192:195], v[110:113]
	v_mfma_f32_16x16x32_bf16 v[106:109], v[62:65], v[192:195], v[106:109]
	v_mfma_f32_16x16x32_bf16 v[94:97], v[50:53], v[200:203], v[94:97]
	v_mfma_f32_16x16x32_bf16 v[90:93], v[62:65], v[200:203], v[90:93]
	v_mfma_f32_16x16x32_bf16 v[142:145], v[54:57], v[180:183], v[142:145]
	v_mfma_f32_16x16x32_bf16 v[138:141], v[70:73], v[180:183], v[138:141]
	v_mfma_f32_16x16x32_bf16 v[126:129], v[54:57], v[188:191], v[126:129]
	v_mfma_f32_16x16x32_bf16 v[122:125], v[70:73], v[188:191], v[122:125]
	v_mfma_f32_16x16x32_bf16 v[110:113], v[54:57], v[196:199], v[110:113]
	v_mfma_f32_16x16x32_bf16 v[106:109], v[70:73], v[196:199], v[106:109]
	v_mfma_f32_16x16x32_bf16 v[94:97], v[54:57], v[204:207], v[94:97]
	v_mfma_f32_16x16x32_bf16 v[90:93], v[70:73], v[204:207], v[90:93]
	s_setprio 0
	s_setprio 1
	v_mfma_f32_16x16x32_bf16 v[134:137], v[156:159], v[176:179], v[134:137]
	v_mfma_f32_16x16x32_bf16 v[130:133], v[168:171], v[176:179], v[130:133]
	v_mfma_f32_16x16x32_bf16 v[118:121], v[156:159], v[184:187], v[118:121]
	v_mfma_f32_16x16x32_bf16 v[114:117], v[168:171], v[184:187], v[114:117]
	v_mfma_f32_16x16x32_bf16 v[102:105], v[156:159], v[192:195], v[102:105]
	v_mfma_f32_16x16x32_bf16 v[98:101], v[168:171], v[192:195], v[98:101]
	v_mfma_f32_16x16x32_bf16 v[86:89], v[156:159], v[200:203], v[86:89]
	v_mfma_f32_16x16x32_bf16 v[82:85], v[168:171], v[200:203], v[82:85]
	v_mfma_f32_16x16x32_bf16 v[134:137], v[160:163], v[180:183], v[134:137]
	v_mfma_f32_16x16x32_bf16 v[130:133], v[172:175], v[180:183], v[130:133]
	v_mfma_f32_16x16x32_bf16 v[118:121], v[160:163], v[188:191], v[118:121]
	v_mfma_f32_16x16x32_bf16 v[114:117], v[172:175], v[188:191], v[114:117]
	v_mfma_f32_16x16x32_bf16 v[102:105], v[160:163], v[196:199], v[102:105]
	v_mfma_f32_16x16x32_bf16 v[98:101], v[172:175], v[196:199], v[98:101]
	v_mfma_f32_16x16x32_bf16 v[86:89], v[160:163], v[204:207], v[86:89]
	v_mfma_f32_16x16x32_bf16 v[82:85], v[172:175], v[204:207], v[82:85]
	s_setprio 0
	s_barrier
	s_add_i32 s100, s68, s47
	s_add_i32 m0, s100, 0xffffff80
	ds_read_b128 v[176:179], v166 offset:49152
	ds_read_b128 v[180:183], v166 offset:50176
	ds_read_b128 v[184:187], v166 offset:51200
	ds_read_b128 v[188:191], v166 offset:52224
	ds_read_b128 v[192:195], v166 offset:53248
	ds_read_b128 v[196:199], v166 offset:54272
	ds_read_b128 v[200:203], v166 offset:55296
	ds_read_b128 v[204:207], v166 offset:56320
	global_load_lds_dwordx4 v0, s[42:43] offset:128
	s_add_i32 m0, s100, 0x1f80
	s_nop 0
	global_load_lds_dwordx4 v146, s[42:43] offset:128
	s_add_u32 s42, s42, 0x40080
	s_addc_u32 s43, s43, 0
	s_add_i32 s100, s69, s47
	s_mov_b32 m0, s100
	s_nop 0
	global_load_lds_dwordx4 v0, s[42:43]
	s_add_i32 m0, s100, 0x2000
	s_nop 0
	global_load_lds_dwordx4 v146, s[42:43]
	s_add_i32 m0, s57, 0xffffff80
	s_nop 0
	global_load_lds_dwordx4 v150, s[44:45] offset:128
	s_add_i32 m0, s58, 0xffffff80
	s_nop 0
	global_load_lds_dwordx4 v148, s[44:45] offset:128
	s_waitcnt vmcnt(8)
	s_waitcnt lgkmcnt(0)
	s_barrier
	s_setprio 1
	s_waitcnt lgkmcnt(0)
	v_mfma_f32_16x16x32_bf16 v[78:81], v[50:53], v[176:179], v[78:81]
	v_mfma_f32_16x16x32_bf16 v[74:77], v[62:65], v[176:179], v[74:77]
	v_mfma_f32_16x16x32_bf16 v[66:69], v[50:53], v[184:187], v[66:69]
	v_mfma_f32_16x16x32_bf16 v[58:61], v[62:65], v[184:187], v[58:61]
	v_mfma_f32_16x16x32_bf16 v[42:45], v[50:53], v[192:195], v[42:45]
	v_mfma_f32_16x16x32_bf16 v[34:37], v[62:65], v[192:195], v[34:37]
	v_mfma_f32_16x16x32_bf16 v[18:21], v[50:53], v[200:203], v[18:21]
	v_mfma_f32_16x16x32_bf16 v[10:13], v[62:65], v[200:203], v[10:13]
	v_mfma_f32_16x16x32_bf16 v[78:81], v[54:57], v[180:183], v[78:81]
	v_mfma_f32_16x16x32_bf16 v[74:77], v[70:73], v[180:183], v[74:77]
	v_mfma_f32_16x16x32_bf16 v[66:69], v[54:57], v[188:191], v[66:69]
	v_mfma_f32_16x16x32_bf16 v[58:61], v[70:73], v[188:191], v[58:61]
	v_mfma_f32_16x16x32_bf16 v[42:45], v[54:57], v[196:199], v[42:45]
	v_mfma_f32_16x16x32_bf16 v[34:37], v[70:73], v[196:199], v[34:37]
	v_mfma_f32_16x16x32_bf16 v[18:21], v[54:57], v[204:207], v[18:21]
	v_mfma_f32_16x16x32_bf16 v[10:13], v[70:73], v[204:207], v[10:13]
	s_setprio 0
	s_setprio 1
	v_mfma_f32_16x16x32_bf16 v[26:29], v[156:159], v[176:179], v[26:29]
	v_mfma_f32_16x16x32_bf16 v[70:73], v[160:163], v[180:183], v[26:29]
	v_mfma_f32_16x16x32_bf16 v[26:29], v[168:171], v[176:179], v[30:33]
	v_mfma_f32_16x16x32_bf16 v[62:65], v[172:175], v[180:183], v[26:29]
	v_mfma_f32_16x16x32_bf16 v[26:29], v[156:159], v[184:187], v[46:49]
	v_mfma_f32_16x16x32_bf16 v[46:49], v[160:163], v[188:191], v[26:29]
	v_mfma_f32_16x16x32_bf16 v[26:29], v[168:171], v[184:187], v[38:41]
	v_mfma_f32_16x16x32_bf16 v[22:25], v[156:159], v[192:195], v[22:25]
	v_mfma_f32_16x16x32_bf16 v[14:17], v[168:171], v[192:195], v[14:17]
	v_mfma_f32_16x16x32_bf16 v[6:9], v[156:159], v[200:203], v[6:9]
	v_mfma_f32_16x16x32_bf16 v[2:5], v[168:171], v[200:203], v[2:5]
	v_mfma_f32_16x16x32_bf16 v[38:41], v[172:175], v[188:191], v[26:29]
	v_mfma_f32_16x16x32_bf16 v[22:25], v[160:163], v[196:199], v[22:25]
	v_mfma_f32_16x16x32_bf16 v[14:17], v[172:175], v[196:199], v[14:17]
	v_mfma_f32_16x16x32_bf16 v[6:9], v[160:163], v[204:207], v[6:9]
	v_mfma_f32_16x16x32_bf16 v[2:5], v[172:175], v[204:207], v[2:5]
	s_setprio 0
	s_barrier
	s_add_i32 s67, s67, 2
	s_add_u32 s38, s38, 0x100
	s_addc_u32 s39, s39, 0
	s_add_u32 s65, s65, 0x100
	s_addc_u32 s66, s66, 0
	s_cmp_gt_u32 s67, 13
	s_cbranch_scc0 .LBB0_30
	s_and_b64 vcc, exec, s[10:11]
	s_cbranch_vccz .LBB0_33
	s_barrier
